# add: hand-written RWKV-7 prompt-scan inner loop (fma-chain dots, SGPR select masks shifted by s_lshl_b64, o/sa DPP reductions interleaved); sample-scan split 0x1800
# speedup vs baseline: 1.0208x; 1.0033x over previous
.LBB0_740:
	v_readlane_b32 s90, v244, 3
	v_readlane_b32 s62, v244, 0
	v_readlane_b32 s58, v245, 58
	v_readlane_b32 s56, v245, 60
	s_bitcmp0_b32 s82, 4
	v_readlane_b32 s88, v244, 7
	v_readlane_b32 s91, v244, 4
	v_readlane_b32 s61, v244, 2
	v_readlane_b32 s63, v244, 1
	v_readlane_b32 s59, v245, 59
	v_readlane_b32 s57, v245, 61
	v_readlane_b32 s60, v244, 8
	s_cbranch_scc1 .LBB0_762
	s_lshl_b32 s0, s92, 3
	s_add_i32 s10, s84, s0
	s_addk_i32 s10, 0x1800
	s_cmpk_gt_i32 s10, 0x7fff
	s_cbranch_scc1 .LBB0_762
	s_add_u32 s0, s96, 0xe800000
	s_addc_u32 s1, s97, 0
	s_add_u32 s8, s96, 0x10a40000
	s_addc_u32 s9, s97, 0
	v_readlane_b32 s12, v245, 6
	s_add_u32 s2, s96, 0x2f00000
	v_readlane_b32 s20, v245, 14
	s_addc_u32 s3, s97, 0
	v_readlane_b32 s13, v245, 7
	v_readlane_b32 s14, v245, 8
	v_readlane_b32 s15, v245, 9
	v_readlane_b32 s21, v245, 15
	s_add_u32 s20, s96, 0x17100000
	v_and_b32_e32 v2, 15, v208
	v_readlane_b32 s23, v245, 17
	s_addc_u32 s21, s97, 0
	v_readlane_b32 s12, v245, 0
	s_lshl_b32 s11, s60, 3
	v_mov_b32_e32 v1, 0
	v_lshlrev_b32_e32 v0, 4, v2
	v_readlane_b32 s18, v245, 12
	v_readlane_b32 s19, v245, 13
	v_readlane_b32 s13, v245, 1
	v_readlane_b32 s14, v245, 2
	v_readlane_b32 s15, v245, 3
	s_sub_i32 s23, 0, s11
	s_lshl_b32 s11, s88, 3
	v_readlane_b32 s24, v245, 18
	s_waitcnt vmcnt(0)
	v_lshl_add_u64 v[18:19], s[18:19], 0, v[0:1]
	v_lshl_add_u64 v[0:1], s[14:15], 0, v[0:1]
	s_mov_b64 s[12:13], 0x4ab1200
	s_add_i32 s11, s84, s11
	v_readlane_b32 s25, v245, 19
	v_readlane_b32 s26, v245, 20
	v_lshl_add_u64 v[20:21], v[0:1], 0, s[12:13]
	s_add_i32 s24, s11, 0x1800
	s_lshl_b32 s11, s33, 3
	s_lshl_b32 s12, s60, 4
	v_readlane_b32 s22, v245, 16
	v_readlane_b32 s27, v245, 21
	s_sub_i32 s25, s11, s12
	s_lshl_b32 s26, s10, 2
	s_lshl_b32 s10, s33, 6
	s_lshl_b32 s11, s60, 6
	v_lshrrev_b32_e32 v17, 4, v179
	v_lshlrev_b32_e32 v16, 2, v2
	v_cmp_ne_u32_e64 s[4:5], 0, v2
	v_cmp_eq_u32_e64 s[6:7], 0, v2
	s_lshl_b32 s22, s76, 4
	s_sub_i32 s27, s10, s11
	v_readlane_b32 s16, v245, 10
	v_readlane_b32 s17, v245, 11
	s_branch .LBB0_744

.LBB0_776:
	v_mov_b32_e32 v91, v80
	v_mov_b32_e32 v92, v70
	v_mov_b32_e32 v93, v79
	s_mov_b32 s18, 0
	s_mov_b32 s64, 0x10001
	s_mov_b32 s65, 0x10001
	s_mov_b32 s66, 0x20002
	s_mov_b32 s67, 0x20002
	s_mov_b32 s68, 0x40004
	s_mov_b32 s69, 0x40004
	s_mov_b32 s70, 0x80008
	s_mov_b32 s71, 0x80008
.LBB0_777:
	ds_read_b128 v[28:31], v91
	ds_read_b128 v[32:35], v91 offset:256
	ds_read_b128 v[40:43], v91 offset:512
	ds_read_b128 v[36:39], v91 offset:768
	ds_read2_b32 v[68:69], v93 offset1:32
	ds_read_b128 v[94:97], v91 offset:1024
	ds_read_b128 v[44:47], v91 offset:1280
	ds_read_b128 v[48:51], v91 offset:1536
	ds_read_b128 v[98:101], v91 offset:1792
	ds_read_b128 v[102:105], v91 offset:2048
	ds_read_b128 v[52:55], v91 offset:2304
	ds_read_b128 v[106:109], v91 offset:2560
	ds_read_b128 v[110:113], v91 offset:2816
	ds_read_b128 v[114:117], v91 offset:3072
	ds_read_b128 v[118:121], v91 offset:3328
	ds_read2_b32 v[146:147], v93 offset0:64 offset1:96
	s_waitcnt lgkmcnt(12)
	v_mul_f32_e32 v148, v24, v36
	v_fma_f32 v148, v25, v37, v148
	v_fma_f32 v148, v26, v38, v148
	v_fma_f32 v148, v27, v39, v148
	ds_read_b128 v[122:125], v91 offset:3584
	ds_read_b128 v[126:129], v91 offset:3840
	ds_read_b128 v[130:133], v91 offset:4096
	ds_read_b128 v[134:137], v91 offset:4352
	ds_read_b128 v[138:141], v91 offset:4608
	ds_read_b128 v[142:145], v91 offset:4864
	s_waitcnt lgkmcnt(15)
	v_mul_f32_e32 v40, v68, v40
	s_nop 0
	v_add_f32_dpp v148, v148, v148 row_ror:8 row_mask:0xf bank_mask:0xf bound_ctrl:1
	s_nop 0
	v_mul_f32_e32 v41, v68, v41
	v_add_f32_dpp v148, v148, v148 row_ror:4 row_mask:0xf bank_mask:0xf bound_ctrl:1
	s_nop 0
	v_mul_f32_e32 v42, v68, v42
	v_add_f32_dpp v148, v148, v148 row_ror:2 row_mask:0xf bank_mask:0xf bound_ctrl:1
	s_nop 0
	v_mul_f32_e32 v43, v68, v43
	v_add_f32_dpp v148, v148, v148 row_ror:1 row_mask:0xf bank_mask:0xf bound_ctrl:1
	s_nop 0
	s_waitcnt lgkmcnt(15)
	v_fma_f32 v40, v148, v94, v40
	v_fma_f32 v41, v148, v95, v41
	v_fma_f32 v42, v148, v96, v42
	v_fma_f32 v43, v148, v97, v43
	v_fma_f32 v24, v24, v32, v40
	v_fma_f32 v25, v25, v33, v41
	v_fma_f32 v26, v26, v34, v42
	v_fma_f32 v27, v27, v35, v43
	s_waitcnt lgkmcnt(12)
	v_mul_f32_e32 v148, v24, v102
	v_mul_f32_e32 v149, v24, v28
	v_fma_f32 v148, v25, v103, v148
	v_fma_f32 v149, v25, v29, v149
	v_fma_f32 v148, v26, v104, v148
	v_fma_f32 v149, v26, v30, v149
	v_fma_f32 v148, v27, v105, v148
	v_fma_f32 v149, v27, v31, v149
	s_waitcnt lgkmcnt(13)
	v_mul_f32_e32 v98, v69, v98
	v_add_f32_dpp v148, v148, v148 row_ror:8 row_mask:0xf bank_mask:0xf bound_ctrl:1
	v_add_f32_dpp v149, v149, v149 row_ror:8 row_mask:0xf bank_mask:0xf bound_ctrl:1
	v_mul_f32_e32 v99, v69, v99
	v_add_f32_dpp v148, v148, v148 row_ror:4 row_mask:0xf bank_mask:0xf bound_ctrl:1
	v_add_f32_dpp v149, v149, v149 row_ror:4 row_mask:0xf bank_mask:0xf bound_ctrl:1
	v_mul_f32_e32 v100, v69, v100
	v_add_f32_dpp v148, v148, v148 row_ror:2 row_mask:0xf bank_mask:0xf bound_ctrl:1
	v_add_f32_dpp v149, v149, v149 row_ror:2 row_mask:0xf bank_mask:0xf bound_ctrl:1
	v_mul_f32_e32 v101, v69, v101
	v_add_f32_dpp v148, v148, v148 row_ror:1 row_mask:0xf bank_mask:0xf bound_ctrl:1
	v_add_f32_dpp v149, v149, v149 row_ror:1 row_mask:0xf bank_mask:0xf bound_ctrl:1
	v_cndmask_b32_e64 v56, v56, v149, s[64:65]
	s_waitcnt lgkmcnt(11)
	v_fma_f32 v98, v148, v52, v98
	v_fma_f32 v99, v148, v53, v99
	v_fma_f32 v100, v148, v54, v100
	v_fma_f32 v101, v148, v55, v101
	v_fma_f32 v24, v24, v48, v98
	v_fma_f32 v25, v25, v49, v99
	v_fma_f32 v26, v26, v50, v100
	v_fma_f32 v27, v27, v51, v101
	s_waitcnt lgkmcnt(7)
	v_mul_f32_e32 v148, v24, v118
	v_mul_f32_e32 v149, v24, v44
	v_fma_f32 v148, v25, v119, v148
	v_fma_f32 v149, v25, v45, v149
	v_fma_f32 v148, v26, v120, v148
	v_fma_f32 v149, v26, v46, v149
	v_fma_f32 v148, v27, v121, v148
	v_fma_f32 v149, v27, v47, v149
	s_waitcnt lgkmcnt(6)
	v_mul_f32_e32 v114, v146, v114
	v_add_f32_dpp v148, v148, v148 row_ror:8 row_mask:0xf bank_mask:0xf bound_ctrl:1
	v_add_f32_dpp v149, v149, v149 row_ror:8 row_mask:0xf bank_mask:0xf bound_ctrl:1
	v_mul_f32_e32 v115, v146, v115
	v_add_f32_dpp v148, v148, v148 row_ror:4 row_mask:0xf bank_mask:0xf bound_ctrl:1
	v_add_f32_dpp v149, v149, v149 row_ror:4 row_mask:0xf bank_mask:0xf bound_ctrl:1
	v_mul_f32_e32 v116, v146, v116
	v_add_f32_dpp v148, v148, v148 row_ror:2 row_mask:0xf bank_mask:0xf bound_ctrl:1
	v_add_f32_dpp v149, v149, v149 row_ror:2 row_mask:0xf bank_mask:0xf bound_ctrl:1
	v_mul_f32_e32 v117, v146, v117
	v_add_f32_dpp v148, v148, v148 row_ror:1 row_mask:0xf bank_mask:0xf bound_ctrl:1
	v_add_f32_dpp v149, v149, v149 row_ror:1 row_mask:0xf bank_mask:0xf bound_ctrl:1
	v_cndmask_b32_e64 v56, v56, v149, s[66:67]
	s_waitcnt lgkmcnt(5)
	v_fma_f32 v114, v148, v122, v114
	v_fma_f32 v115, v148, v123, v115
	v_fma_f32 v116, v148, v124, v116
	v_fma_f32 v117, v148, v125, v117
	v_fma_f32 v24, v24, v110, v114
	v_fma_f32 v25, v25, v111, v115
	v_fma_f32 v26, v26, v112, v116
	v_fma_f32 v27, v27, v113, v117
	s_waitcnt lgkmcnt(1)
	v_mul_f32_e32 v148, v24, v138
	v_mul_f32_e32 v149, v24, v106
	v_fma_f32 v148, v25, v139, v148
	v_fma_f32 v149, v25, v107, v149
	v_fma_f32 v148, v26, v140, v148
	v_fma_f32 v149, v26, v108, v149
	v_fma_f32 v148, v27, v141, v148
	v_fma_f32 v149, v27, v109, v149
	s_waitcnt lgkmcnt(2)
	v_mul_f32_e32 v134, v147, v134
	v_add_f32_dpp v148, v148, v148 row_ror:8 row_mask:0xf bank_mask:0xf bound_ctrl:1
	v_add_f32_dpp v149, v149, v149 row_ror:8 row_mask:0xf bank_mask:0xf bound_ctrl:1
	v_mul_f32_e32 v135, v147, v135
	v_add_f32_dpp v148, v148, v148 row_ror:4 row_mask:0xf bank_mask:0xf bound_ctrl:1
	v_add_f32_dpp v149, v149, v149 row_ror:4 row_mask:0xf bank_mask:0xf bound_ctrl:1
	v_mul_f32_e32 v136, v147, v136
	v_add_f32_dpp v148, v148, v148 row_ror:2 row_mask:0xf bank_mask:0xf bound_ctrl:1
	v_add_f32_dpp v149, v149, v149 row_ror:2 row_mask:0xf bank_mask:0xf bound_ctrl:1
	v_mul_f32_e32 v137, v147, v137
	v_add_f32_dpp v148, v148, v148 row_ror:1 row_mask:0xf bank_mask:0xf bound_ctrl:1
	v_add_f32_dpp v149, v149, v149 row_ror:1 row_mask:0xf bank_mask:0xf bound_ctrl:1
	v_cndmask_b32_e64 v56, v56, v149, s[68:69]
	s_waitcnt lgkmcnt(0)
	v_fma_f32 v134, v148, v142, v134
	v_fma_f32 v135, v148, v143, v135
	v_fma_f32 v136, v148, v144, v136
	v_fma_f32 v137, v148, v145, v137
	v_fma_f32 v24, v24, v130, v134
	v_fma_f32 v25, v25, v131, v135
	v_fma_f32 v26, v26, v132, v136
	v_fma_f32 v27, v27, v133, v137
	s_waitcnt lgkmcnt(4)
	v_mul_f32_e32 v149, v24, v126
	v_fma_f32 v149, v25, v127, v149
	v_fma_f32 v149, v26, v128, v149
	v_fma_f32 v149, v27, v129, v149
	s_nop 1
	v_add_f32_dpp v149, v149, v149 row_ror:8 row_mask:0xf bank_mask:0xf bound_ctrl:1
	s_nop 1
	v_add_f32_dpp v149, v149, v149 row_ror:4 row_mask:0xf bank_mask:0xf bound_ctrl:1
	s_nop 1
	v_add_f32_dpp v149, v149, v149 row_ror:2 row_mask:0xf bank_mask:0xf bound_ctrl:1
	s_nop 1
	v_add_f32_dpp v149, v149, v149 row_ror:1 row_mask:0xf bank_mask:0xf bound_ctrl:1
	s_add_i32 s18, s18, 4
	v_add_u32_e32 v93, 0x200, v93
	v_add_u32_e32 v91, 0x1400, v91
	v_cndmask_b32_e64 v56, v56, v149, s[70:71]
	s_lshl_b64 s[64:65], s[64:65], 4
	s_lshl_b64 s[66:67], s[66:67], 4
	s_lshl_b64 s[68:69], s[68:69], 4
	s_lshl_b64 s[70:71], s[70:71], 4
	s_cmp_eq_u32 s18, 16
	s_cbranch_scc0 .LBB0_777
	s_cmpk_lg_i32 s13, 0x80
	s_cbranch_scc0 .LBB0_782
	s_and_saveexec_b64 s[0:1], vcc
	s_cbranch_execz .LBB0_781
	s_waitcnt vmcnt(3)
	v_lshlrev_b32_e32 v28, 16, v8
	v_lshlrev_b32_e32 v29, 16, v10
	v_lshlrev_b32_e32 v30, 16, v4
	v_lshlrev_b32_e32 v31, 16, v6
	v_and_b32_e32 v32, 0xffff0000, v8
	v_and_b32_e32 v33, 0xffff0000, v10
	v_and_b32_e32 v34, 0xffff0000, v4
	v_and_b32_e32 v35, 0xffff0000, v6
	v_lshlrev_b32_e32 v36, 16, v9
	v_lshlrev_b32_e32 v37, 16, v11
	v_lshlrev_b32_e32 v38, 16, v5
	v_lshlrev_b32_e32 v39, 16, v7
	v_and_b32_e32 v40, 0xffff0000, v9
	v_and_b32_e32 v41, 0xffff0000, v11
	v_and_b32_e32 v42, 0xffff0000, v5
	v_and_b32_e32 v43, 0xffff0000, v7
	ds_write_b128 v75, v[28:31] offset:20480
	ds_write_b128 v75, v[0:3] offset:20736
	ds_write_b128 v75, v[32:35] offset:20992
	ds_write_b128 v75, v[36:39] offset:21248
	ds_write_b128 v75, v[40:43] offset:21504

.LBB0_786:
	v_add_u32_e32 v28, s18, v88
	v_ashrrev_i32_e32 v29, 31, v28
	v_lshlrev_b64 v[28:29], 12, v[28:29]
	s_or_b32 s19, s13, 1
	v_lshl_add_u64 v[28:29], v[66:67], 0, v[28:29]
	s_cmpk_gt_u32 s19, 0x80
	global_store_dword v[28:29], v56, off
	s_waitcnt lgkmcnt(0)
	s_barrier
	s_cbranch_scc1 .LBB0_796
	s_mov_b32 s20, 0
	v_mov_b32_e32 v91, v82
	v_mov_b32_e32 v92, v70
	v_mov_b32_e32 v93, v81
	s_mov_b32 s64, 0x10001
	s_mov_b32 s65, 0x10001
	s_mov_b32 s66, 0x20002
	s_mov_b32 s67, 0x20002
	s_mov_b32 s68, 0x40004
	s_mov_b32 s69, 0x40004
	s_mov_b32 s70, 0x80008
	s_mov_b32 s71, 0x80008
.LBB0_788:
	ds_read_b128 v[28:31], v91
	ds_read_b128 v[32:35], v91 offset:256
	ds_read_b128 v[40:43], v91 offset:512
	ds_read_b128 v[36:39], v91 offset:768
	ds_read2_b32 v[68:69], v93 offset1:32
	ds_read_b128 v[94:97], v91 offset:1024
	ds_read_b128 v[44:47], v91 offset:1280
	ds_read_b128 v[48:51], v91 offset:1536
	ds_read_b128 v[98:101], v91 offset:1792
	ds_read_b128 v[102:105], v91 offset:2048
	ds_read_b128 v[52:55], v91 offset:2304
	ds_read_b128 v[106:109], v91 offset:2560
	ds_read_b128 v[110:113], v91 offset:2816
	ds_read_b128 v[114:117], v91 offset:3072
	ds_read_b128 v[118:121], v91 offset:3328
	ds_read2_b32 v[146:147], v93 offset0:64 offset1:96
	s_waitcnt lgkmcnt(12)
	v_mul_f32_e32 v148, v24, v36
	v_fma_f32 v148, v25, v37, v148
	v_fma_f32 v148, v26, v38, v148
	v_fma_f32 v148, v27, v39, v148
	ds_read_b128 v[122:125], v91 offset:3584
	ds_read_b128 v[126:129], v91 offset:3840
	ds_read_b128 v[130:133], v91 offset:4096
	ds_read_b128 v[134:137], v91 offset:4352
	ds_read_b128 v[138:141], v91 offset:4608
	ds_read_b128 v[142:145], v91 offset:4864
	s_waitcnt lgkmcnt(15)
	v_mul_f32_e32 v40, v68, v40
	s_nop 0
	v_add_f32_dpp v148, v148, v148 row_ror:8 row_mask:0xf bank_mask:0xf bound_ctrl:1
	s_nop 0
	v_mul_f32_e32 v41, v68, v41
	v_add_f32_dpp v148, v148, v148 row_ror:4 row_mask:0xf bank_mask:0xf bound_ctrl:1
	s_nop 0
	v_mul_f32_e32 v42, v68, v42
	v_add_f32_dpp v148, v148, v148 row_ror:2 row_mask:0xf bank_mask:0xf bound_ctrl:1
	s_nop 0
	v_mul_f32_e32 v43, v68, v43
	v_add_f32_dpp v148, v148, v148 row_ror:1 row_mask:0xf bank_mask:0xf bound_ctrl:1
	s_nop 0
	s_waitcnt lgkmcnt(15)
	v_fma_f32 v40, v148, v94, v40
	v_fma_f32 v41, v148, v95, v41
	v_fma_f32 v42, v148, v96, v42
	v_fma_f32 v43, v148, v97, v43
	v_fma_f32 v24, v24, v32, v40
	v_fma_f32 v25, v25, v33, v41
	v_fma_f32 v26, v26, v34, v42
	v_fma_f32 v27, v27, v35, v43
	s_waitcnt lgkmcnt(12)
	v_mul_f32_e32 v148, v24, v102
	v_mul_f32_e32 v149, v24, v28
	v_fma_f32 v148, v25, v103, v148
	v_fma_f32 v149, v25, v29, v149
	v_fma_f32 v148, v26, v104, v148
	v_fma_f32 v149, v26, v30, v149
	v_fma_f32 v148, v27, v105, v148
	v_fma_f32 v149, v27, v31, v149
	s_waitcnt lgkmcnt(13)
	v_mul_f32_e32 v98, v69, v98
	v_add_f32_dpp v148, v148, v148 row_ror:8 row_mask:0xf bank_mask:0xf bound_ctrl:1
	v_add_f32_dpp v149, v149, v149 row_ror:8 row_mask:0xf bank_mask:0xf bound_ctrl:1
	v_mul_f32_e32 v99, v69, v99
	v_add_f32_dpp v148, v148, v148 row_ror:4 row_mask:0xf bank_mask:0xf bound_ctrl:1
	v_add_f32_dpp v149, v149, v149 row_ror:4 row_mask:0xf bank_mask:0xf bound_ctrl:1
	v_mul_f32_e32 v100, v69, v100
	v_add_f32_dpp v148, v148, v148 row_ror:2 row_mask:0xf bank_mask:0xf bound_ctrl:1
	v_add_f32_dpp v149, v149, v149 row_ror:2 row_mask:0xf bank_mask:0xf bound_ctrl:1
	v_mul_f32_e32 v101, v69, v101
	v_add_f32_dpp v148, v148, v148 row_ror:1 row_mask:0xf bank_mask:0xf bound_ctrl:1
	v_add_f32_dpp v149, v149, v149 row_ror:1 row_mask:0xf bank_mask:0xf bound_ctrl:1
	v_cndmask_b32_e64 v56, v56, v149, s[64:65]
	s_waitcnt lgkmcnt(11)
	v_fma_f32 v98, v148, v52, v98
	v_fma_f32 v99, v148, v53, v99
	v_fma_f32 v100, v148, v54, v100
	v_fma_f32 v101, v148, v55, v101
	v_fma_f32 v24, v24, v48, v98
	v_fma_f32 v25, v25, v49, v99
	v_fma_f32 v26, v26, v50, v100
	v_fma_f32 v27, v27, v51, v101
	s_waitcnt lgkmcnt(7)
	v_mul_f32_e32 v148, v24, v118
	v_mul_f32_e32 v149, v24, v44
	v_fma_f32 v148, v25, v119, v148
	v_fma_f32 v149, v25, v45, v149
	v_fma_f32 v148, v26, v120, v148
	v_fma_f32 v149, v26, v46, v149
	v_fma_f32 v148, v27, v121, v148
	v_fma_f32 v149, v27, v47, v149
	s_waitcnt lgkmcnt(6)
	v_mul_f32_e32 v114, v146, v114
	v_add_f32_dpp v148, v148, v148 row_ror:8 row_mask:0xf bank_mask:0xf bound_ctrl:1
	v_add_f32_dpp v149, v149, v149 row_ror:8 row_mask:0xf bank_mask:0xf bound_ctrl:1
	v_mul_f32_e32 v115, v146, v115
	v_add_f32_dpp v148, v148, v148 row_ror:4 row_mask:0xf bank_mask:0xf bound_ctrl:1
	v_add_f32_dpp v149, v149, v149 row_ror:4 row_mask:0xf bank_mask:0xf bound_ctrl:1
	v_mul_f32_e32 v116, v146, v116
	v_add_f32_dpp v148, v148, v148 row_ror:2 row_mask:0xf bank_mask:0xf bound_ctrl:1
	v_add_f32_dpp v149, v149, v149 row_ror:2 row_mask:0xf bank_mask:0xf bound_ctrl:1
	v_mul_f32_e32 v117, v146, v117
	v_add_f32_dpp v148, v148, v148 row_ror:1 row_mask:0xf bank_mask:0xf bound_ctrl:1
	v_add_f32_dpp v149, v149, v149 row_ror:1 row_mask:0xf bank_mask:0xf bound_ctrl:1
	v_cndmask_b32_e64 v56, v56, v149, s[66:67]
	s_waitcnt lgkmcnt(5)
	v_fma_f32 v114, v148, v122, v114
	v_fma_f32 v115, v148, v123, v115
	v_fma_f32 v116, v148, v124, v116
	v_fma_f32 v117, v148, v125, v117
	v_fma_f32 v24, v24, v110, v114
	v_fma_f32 v25, v25, v111, v115
	v_fma_f32 v26, v26, v112, v116
	v_fma_f32 v27, v27, v113, v117
	s_waitcnt lgkmcnt(1)
	v_mul_f32_e32 v148, v24, v138
	v_mul_f32_e32 v149, v24, v106
	v_fma_f32 v148, v25, v139, v148
	v_fma_f32 v149, v25, v107, v149
	v_fma_f32 v148, v26, v140, v148
	v_fma_f32 v149, v26, v108, v149
	v_fma_f32 v148, v27, v141, v148
	v_fma_f32 v149, v27, v109, v149
	s_waitcnt lgkmcnt(2)
	v_mul_f32_e32 v134, v147, v134
	v_add_f32_dpp v148, v148, v148 row_ror:8 row_mask:0xf bank_mask:0xf bound_ctrl:1
	v_add_f32_dpp v149, v149, v149 row_ror:8 row_mask:0xf bank_mask:0xf bound_ctrl:1
	v_mul_f32_e32 v135, v147, v135
	v_add_f32_dpp v148, v148, v148 row_ror:4 row_mask:0xf bank_mask:0xf bound_ctrl:1
	v_add_f32_dpp v149, v149, v149 row_ror:4 row_mask:0xf bank_mask:0xf bound_ctrl:1
	v_mul_f32_e32 v136, v147, v136
	v_add_f32_dpp v148, v148, v148 row_ror:2 row_mask:0xf bank_mask:0xf bound_ctrl:1
	v_add_f32_dpp v149, v149, v149 row_ror:2 row_mask:0xf bank_mask:0xf bound_ctrl:1
	v_mul_f32_e32 v137, v147, v137
	v_add_f32_dpp v148, v148, v148 row_ror:1 row_mask:0xf bank_mask:0xf bound_ctrl:1
	v_add_f32_dpp v149, v149, v149 row_ror:1 row_mask:0xf bank_mask:0xf bound_ctrl:1
	v_cndmask_b32_e64 v56, v56, v149, s[68:69]
	s_waitcnt lgkmcnt(0)
	v_fma_f32 v134, v148, v142, v134
	v_fma_f32 v135, v148, v143, v135
	v_fma_f32 v136, v148, v144, v136
	v_fma_f32 v137, v148, v145, v137
	v_fma_f32 v24, v24, v130, v134
	v_fma_f32 v25, v25, v131, v135
	v_fma_f32 v26, v26, v132, v136
	v_fma_f32 v27, v27, v133, v137
	s_waitcnt lgkmcnt(4)
	v_mul_f32_e32 v149, v24, v126
	v_fma_f32 v149, v25, v127, v149
	v_fma_f32 v149, v26, v128, v149
	v_fma_f32 v149, v27, v129, v149
	s_nop 1
	v_add_f32_dpp v149, v149, v149 row_ror:8 row_mask:0xf bank_mask:0xf bound_ctrl:1
	s_nop 1
	v_add_f32_dpp v149, v149, v149 row_ror:4 row_mask:0xf bank_mask:0xf bound_ctrl:1
	s_nop 1
	v_add_f32_dpp v149, v149, v149 row_ror:2 row_mask:0xf bank_mask:0xf bound_ctrl:1
	s_nop 1
	v_add_f32_dpp v149, v149, v149 row_ror:1 row_mask:0xf bank_mask:0xf bound_ctrl:1
	s_add_i32 s20, s20, 4
	v_add_u32_e32 v93, 0x200, v93
	v_add_u32_e32 v91, 0x1400, v91
	v_cndmask_b32_e64 v56, v56, v149, s[70:71]
	s_lshl_b64 s[64:65], s[64:65], 4
	s_lshl_b64 s[66:67], s[66:67], 4
	s_lshl_b64 s[68:69], s[68:69], 4
	s_lshl_b64 s[70:71], s[70:71], 4
	s_cmp_lg_u32 s20, 16
	s_cbranch_scc1 .LBB0_788
	s_and_saveexec_b64 s[0:1], vcc
	s_cbranch_execz .LBB0_791
	s_waitcnt vmcnt(3)
	v_lshlrev_b32_e32 v28, 16, v20
	v_lshlrev_b32_e32 v29, 16, v22
	v_lshlrev_b32_e32 v30, 16, v16
	v_lshlrev_b32_e32 v31, 16, v18
	v_and_b32_e32 v32, 0xffff0000, v20
	v_and_b32_e32 v33, 0xffff0000, v22
	v_and_b32_e32 v34, 0xffff0000, v16
	v_and_b32_e32 v35, 0xffff0000, v18
	v_lshlrev_b32_e32 v36, 16, v21
	v_lshlrev_b32_e32 v37, 16, v23
	v_lshlrev_b32_e32 v38, 16, v17
	v_lshlrev_b32_e32 v39, 16, v19
	v_and_b32_e32 v40, 0xffff0000, v21
	v_and_b32_e32 v41, 0xffff0000, v23
	v_and_b32_e32 v42, 0xffff0000, v17
	v_and_b32_e32 v43, 0xffff0000, v19
	ds_write_b128 v75, v[28:31]
	ds_write_b128 v75, v[12:15] offset:256
	ds_write_b128 v75, v[32:35] offset:512
	ds_write_b128 v75, v[36:39] offset:768
	ds_write_b128 v75, v[40:43] offset:1024

.LBB0_798:
	s_bitcmp0_b32 s82, 4
	s_cbranch_scc1 .LBB0_820
	s_lshl_b32 s0, s88, 3
	s_add_i32 s2, s84, s0
	s_cmp_gt_i32 s2, 0x17ff
	s_cbranch_scc1 .LBB0_820
	v_readlane_b32 s4, v245, 6
	s_lshl_b32 s3, s60, 3
	v_readlane_b32 s6, v245, 8
	v_readlane_b32 s7, v245, 9
	s_add_u32 s6, s96, 0xe800000
	v_readlane_b32 s8, v245, 10
	s_addc_u32 s7, s97, 0
	v_readlane_b32 s9, v245, 11
	s_add_u32 s8, s96, 0x10a40000
	v_readlane_b32 s12, v245, 14
	v_readlane_b32 s13, v245, 15
	v_readlane_b32 s14, v245, 16
	v_readlane_b32 s15, v245, 17
	s_addc_u32 s9, s97, 0
	s_add_u32 s20, s96, 0x2f00000
	v_readlane_b32 s12, v245, 0
	s_waitcnt vmcnt(5)
	v_mov_b32_e32 v1, 0
	v_lshlrev_b32_e32 v0, 4, v70
	v_readlane_b32 s10, v245, 12
	v_readlane_b32 s11, v245, 13
	s_addc_u32 s21, s97, 0
	v_readlane_b32 s14, v245, 2
	v_readlane_b32 s15, v245, 3
	v_lshl_add_u64 v[18:19], s[10:11], 0, v[0:1]
	s_add_u32 s22, s96, 0x17100000
	v_lshl_add_u64 v[0:1], s[14:15], 0, v[0:1]
	s_mov_b64 s[10:11], 0x4ab1200
	v_readlane_b32 s5, v245, 7
	s_addc_u32 s23, s97, 0
	s_waitcnt vmcnt(4)
	v_lshl_add_u64 v[20:21], v[0:1], 0, s[10:11]
	s_lshl_b32 s10, s88, 5
	s_lshl_b32 s11, s84, 2
	v_lshlrev_b32_e32 v16, 2, v70
	v_cmp_ne_u32_e64 s[0:1], 0, v70
	v_cmp_eq_u32_e64 s[4:5], 0, v70
	s_lshl_b32 s24, s60, 4
	s_add_i32 s25, s10, s11
	s_lshl_b32 s26, s60, 6
	v_readlane_b32 s16, v245, 18
	v_readlane_b32 s17, v245, 19
	v_readlane_b32 s18, v245, 20
	v_readlane_b32 s19, v245, 21
	v_readlane_b32 s13, v245, 1
	s_branch .LBB0_802
.LBB0_801:
	s_add_i32 s2, s2, s24
	s_add_i32 s25, s25, s26
	s_cmp_gt_i32 s2, 0x17ff
	s_cbranch_scc1 .LBB0_820
.LBB0_802:
	s_ashr_i32 s29, s2, 8
	s_lshl_b32 s10, s29, 10
	s_and_b32 s28, s25, 0x3c0
	v_readlane_b32 s36, v245, 6
	s_or_b32 s34, s28, s10
	s_mul_i32 s11, s29, 0x3480
	v_readlane_b32 s40, v245, 10
	s_mul_hi_i32 s10, s29, 0x3480
	v_readlane_b32 s41, v245, 11
	s_add_u32 s14, s40, s11
	s_addc_u32 s15, s41, s10
	s_add_i32 s18, s3, s2
	s_cmp_lt_i32 s18, 0x1800
	s_cselect_b64 s[10:11], -1, 0
	s_cmp_gt_i32 s18, 0x17ff
	s_cselect_b64 s[12:13], -1, 0
	s_and_b64 s[16:17], s[12:13], exec
	s_cselect_b32 s16, s2, s18
	s_ashr_i32 s35, s16, 8
	s_lshl_b32 s36, s16, 2
	v_readlane_b32 s37, v245, 7
	s_lshl_b32 s16, s35, 10
	s_and_b32 s27, s36, 0x3c0
	s_or_b32 s37, s27, s16
	s_mul_i32 s17, s35, 0x3480
	s_mul_hi_i32 s16, s35, 0x3480
	s_add_u32 s18, s40, s17
	s_addc_u32 s19, s41, s16
	s_lshl_b32 s29, s29, 2
	s_add_i32 s16, s29, 0x2040
	s_ashr_i32 s17, s16, 31
	s_lshl_b64 s[30:31], s[16:17], 10
	s_or_b32 s30, s30, s28
	v_mov_b32_e32 v5, s31
	v_or_b32_e32 v4, s30, v16
	v_lshl_add_u64 v[0:1], v[4:5], 3, s[8:9]
	v_and_or_b32 v29, s25, 60, v61
	global_load_dwordx4 v[38:41], v[0:1], off
	global_load_dwordx4 v[42:45], v[0:1], off offset:16
	v_or_b32_e32 v0, s34, v29
	v_ashrrev_i32_e32 v1, 31, v0
	v_readlane_b32 s42, v245, 12
	v_readlane_b32 s43, v245, 13
	v_readlane_b32 s44, v245, 14
	v_readlane_b32 s45, v245, 15
	v_readlane_b32 s46, v245, 16
	v_readlane_b32 s47, v245, 17
	v_readlane_b32 s48, v245, 18
	v_readlane_b32 s49, v245, 19
	v_readlane_b32 s50, v245, 20
	v_readlane_b32 s51, v245, 21
	v_lshlrev_b64 v[22:23], 8, v[0:1]
	v_or_b32_e32 v0, s28, v29
	v_or_b32_e32 v0, 0x800, v0
	s_mul_i32 s30, s16, 0x3480
	v_readlane_b32 s40, v245, 22
	v_lshlrev_b32_e32 v27, 2, v0
	s_mul_hi_i32 s31, s16, 0x3480
	s_add_u32 s30, s20, s30
	v_readlane_b32 s41, v245, 23
	s_addc_u32 s31, s21, s31
	s_nop 3
	global_load_dword v26, v27, s[40:41]
	global_load_dword v33, v27, s[14:15]
	global_load_dword v32, v27, s[30:31]
	s_lshl_b32 s30, s35, 2
	s_add_i32 s14, s30, 0x2040
	v_lshl_add_u64 v[0:1], v[18:19], 0, v[22:23]
	v_and_or_b32 v30, s36, 60, v61
	s_ashr_i32 s15, s14, 31
	global_load_dwordx4 v[46:49], v[0:1], off
	v_or_b32_e32 v0, s37, v30
	s_lshl_b64 s[34:35], s[14:15], 10
	v_ashrrev_i32_e32 v1, 31, v0
	v_or_b32_e32 v6, s27, v30
	v_lshl_add_u64 v[4:5], v[4:5], 2, s[6:7]
	s_or_b32 s31, s34, s27
	v_lshlrev_b64 v[24:25], 8, v[0:1]
	v_or_b32_e32 v6, 0x800, v6
	global_load_dwordx4 v[50:53], v[4:5], off
	v_mov_b32_e32 v5, s35
	v_or_b32_e32 v4, s31, v16
	s_mul_i32 s34, s14, 0x3480
	v_lshl_add_u64 v[0:1], v[18:19], 0, v[24:25]
	v_lshlrev_b32_e32 v28, 2, v6
	v_lshl_add_u64 v[6:7], v[4:5], 2, s[6:7]
	v_lshl_add_u64 v[12:13], v[4:5], 3, s[8:9]
	s_mul_hi_i32 s31, s14, 0x3480
	s_add_u32 s34, s20, s34
	global_load_dwordx4 v[0:3], v[0:1], off
	s_nop 0
	global_load_dwordx4 v[8:11], v[12:13], off offset:16
	s_nop 0
	global_load_dwordx4 v[4:7], v[6:7], off
	s_nop 0
	global_load_dwordx4 v[12:15], v[12:13], off
	s_addc_u32 s35, s21, s31
	global_load_dword v17, v28, s[40:41]
	global_load_dword v37, v28, s[18:19]
	global_load_dword v31, v28, s[34:35]
	s_add_i32 s64, s29, 0x2041
	s_ashr_i32 s65, s64, 31
	s_lshl_b64 s[66:67], s[64:65], 10
	v_mov_b32_e32 v236, s28
	v_or3_b32 v236, s66, v236, v16
	v_or3_b32 v237, s67, 0, 0
	s_mul_hi_i32 s67, s64, 0x3480
	s_mul_i32 s66, s64, 0x3480
	s_add_u32 s66, s20, s66
	s_addc_u32 s67, s21, s67
	v_lshl_add_u64 v[238:239], v[236:237], 3, s[8:9]
	global_load_dwordx4 v[148:151], v[238:239], off
	global_load_dwordx4 v[152:155], v[238:239], off offset:16
	global_load_dword v172, v27, s[66:67]
	v_lshl_add_u64 v[238:239], v[236:237], 2, s[6:7]
	global_load_dwordx4 v[156:159], v[238:239], off
	s_add_i32 s64, s30, 0x2041
	s_ashr_i32 s65, s64, 31
	s_lshl_b64 s[66:67], s[64:65], 10
	v_mov_b32_e32 v236, s27
	v_or3_b32 v236, s66, v236, v16
	v_or3_b32 v237, s67, 0, 0
	s_mul_hi_i32 s67, s64, 0x3480
	s_mul_i32 s66, s64, 0x3480
	s_add_u32 s66, s20, s66
	s_addc_u32 s67, s21, s67
	v_lshl_add_u64 v[238:239], v[236:237], 3, s[8:9]
	global_load_dwordx4 v[160:163], v[238:239], off
	global_load_dwordx4 v[164:167], v[238:239], off offset:16
	global_load_dword v173, v28, s[66:67]
	v_lshl_add_u64 v[238:239], v[236:237], 2, s[6:7]
	global_load_dwordx4 v[168:171], v[238:239], off
	s_add_i32 s64, s29, 0x2042
	s_ashr_i32 s65, s64, 31
	s_lshl_b64 s[66:67], s[64:65], 10
	v_mov_b32_e32 v236, s28
	v_or3_b32 v236, s66, v236, v16
	v_or3_b32 v237, s67, 0, 0
	s_mul_hi_i32 s67, s64, 0x3480
	s_mul_i32 s66, s64, 0x3480
	s_add_u32 s66, s20, s66
	s_addc_u32 s67, s21, s67
	v_lshl_add_u64 v[238:239], v[236:237], 3, s[8:9]
	global_load_dwordx4 v[180:183], v[238:239], off
	global_load_dwordx4 v[184:187], v[238:239], off offset:16
	global_load_dword v204, v27, s[66:67]
	v_lshl_add_u64 v[238:239], v[236:237], 2, s[6:7]
	global_load_dwordx4 v[188:191], v[238:239], off
	s_add_i32 s64, s30, 0x2042
	s_ashr_i32 s65, s64, 31
	s_lshl_b64 s[66:67], s[64:65], 10
	v_mov_b32_e32 v236, s27
	v_or3_b32 v236, s66, v236, v16
	v_or3_b32 v237, s67, 0, 0
	s_mul_hi_i32 s67, s64, 0x3480
	s_mul_i32 s66, s64, 0x3480
	s_add_u32 s66, s20, s66
	s_addc_u32 s67, s21, s67
	v_lshl_add_u64 v[238:239], v[236:237], 3, s[8:9]
	global_load_dwordx4 v[192:195], v[238:239], off
	global_load_dwordx4 v[196:199], v[238:239], off offset:16
	global_load_dword v205, v28, s[66:67]
	v_lshl_add_u64 v[238:239], v[236:237], 2, s[6:7]
	global_load_dwordx4 v[200:203], v[238:239], off
	s_add_i32 s64, s29, 0x2043
	s_ashr_i32 s65, s64, 31
	s_lshl_b64 s[66:67], s[64:65], 10
	v_mov_b32_e32 v236, s28
	v_or3_b32 v236, s66, v236, v16
	v_or3_b32 v237, s67, 0, 0
	s_mul_hi_i32 s67, s64, 0x3480
	s_mul_i32 s66, s64, 0x3480
	s_add_u32 s66, s20, s66
	s_addc_u32 s67, s21, s67
	v_lshl_add_u64 v[238:239], v[236:237], 3, s[8:9]
	global_load_dwordx4 v[210:213], v[238:239], off
	global_load_dwordx4 v[214:217], v[238:239], off offset:16
	global_load_dword v234, v27, s[66:67]
	v_lshl_add_u64 v[238:239], v[236:237], 2, s[6:7]
	global_load_dwordx4 v[218:221], v[238:239], off
	s_add_i32 s64, s30, 0x2043
	s_ashr_i32 s65, s64, 31
	s_lshl_b64 s[66:67], s[64:65], 10
	v_mov_b32_e32 v236, s27
	v_or3_b32 v236, s66, v236, v16
	v_or3_b32 v237, s67, 0, 0
	s_mul_hi_i32 s67, s64, 0x3480
	s_mul_i32 s66, s64, 0x3480
	s_add_u32 s66, s20, s66
	s_addc_u32 s67, s21, s67
	v_lshl_add_u64 v[238:239], v[236:237], 3, s[8:9]
	global_load_dwordx4 v[222:225], v[238:239], off
	global_load_dwordx4 v[226:229], v[238:239], off offset:16
	global_load_dword v235, v28, s[66:67]
	v_lshl_add_u64 v[238:239], v[236:237], 2, s[6:7]
	global_load_dwordx4 v[230:233], v[238:239], off
	v_lshlrev_b32_e32 v29, 2, v29
	v_readlane_b32 s38, v245, 8
	v_readlane_b32 s39, v245, 9
	v_readlane_b32 s42, v245, 24
	v_readlane_b32 s43, v245, 25
	v_readlane_b32 s44, v245, 26
	v_readlane_b32 s45, v245, 27
	v_readlane_b32 s46, v245, 28
	v_readlane_b32 s47, v245, 29
	v_readlane_b32 s48, v245, 30
	v_readlane_b32 s49, v245, 31
	v_readlane_b32 s50, v245, 32
	v_readlane_b32 s51, v245, 33
	v_readlane_b32 s52, v245, 34
	v_readlane_b32 s53, v245, 35
	v_readlane_b32 s54, v245, 36
	v_readlane_b32 s55, v245, 37
	s_waitcnt vmcnt(37)
	v_lshlrev_b32_e32 v55, 16, v40
	v_and_b32_e32 v35, 0xffff0000, v40
	v_lshlrev_b32_e32 v40, 16, v39
	v_lshlrev_b32_e32 v54, 16, v38
	s_waitcnt vmcnt(36)
	v_lshlrev_b32_e32 v56, 16, v42
	v_lshlrev_b32_e32 v57, 16, v44
	v_and_b32_e32 v34, 0xffff0000, v38
	v_and_b32_e32 v36, 0xffff0000, v42
	v_and_b32_e32 v38, 0xffff0000, v44
	v_lshlrev_b32_e32 v42, 16, v41
	v_lshlrev_b32_e32 v44, 16, v43
	v_lshlrev_b32_e32 v58, 16, v45
	v_and_b32_e32 v39, 0xffff0000, v39
	v_and_b32_e32 v41, 0xffff0000, v41
	v_and_b32_e32 v43, 0xffff0000, v43
	v_and_b32_e32 v45, 0xffff0000, v45
	s_waitcnt vmcnt(33)
	v_sub_f32_e32 v33, v33, v32
	v_fma_f32 v59, v26, v33, v32
	s_waitcnt vmcnt(32)
	v_mul_f32 v33, v46, v40
	v_mul_f32 v40, v48, v44
	v_mul_f32 v34, v59, v34
	v_mul_f32 v35, v59, v35
	s_nop 0
	v_fma_f32 v33, v47, v42, v33
	v_fma_f32 v40, v49, v58, v40
	s_nop 0
	v_add_f32 v33, v33, v40
	s_nop 1
	v_add_f32_dpp v33, v33, v33 row_ror:8 row_mask:0xf bank_mask:0xf bound_ctrl:1
	s_nop 1
	v_add_f32_dpp v33, v33, v33 row_ror:4 row_mask:0xf bank_mask:0xf bound_ctrl:1
	s_nop 1
	v_add_f32_dpp v33, v33, v33 row_ror:2 row_mask:0xf bank_mask:0xf bound_ctrl:1
	s_nop 1
	v_add_f32_dpp v40, v33, v33 row_ror:1 row_mask:0xf bank_mask:0xf bound_ctrl:1
	v_fma_f32 v33, v40, v39, v34
	v_fma_f32 v34, v40, v41, v35
	v_mul_f32 v35, v59, v36
	v_mul_f32 v36, v59, v38
	s_waitcnt vmcnt(31)
	v_fma_f32 v33, v46, v50, v33
	v_fma_f32 v35, v40, v43, v35
	v_fma_f32 v34, v47, v51, v34
	v_fma_f32 v36, v40, v45, v36
	s_nop 0
	v_mul_f32 v38, v33, v54
	v_fma_f32 v35, v48, v52, v35
	v_fma_f32 v36, v49, v53, v36
	s_nop 0
	v_fma_f32 v38, v34, v55, v38
	v_mul_f32 v39, v35, v56
	s_nop 0
	v_fma_f32 v39, v36, v57, v39
	s_nop 0
	v_add_f32 v38, v38, v39
	v_mov_b32_e32 v39, 0
	s_nop 0
	v_add_f32_dpp v38, v38, v38 row_ror:8 row_mask:0xf bank_mask:0xf bound_ctrl:1
	s_nop 1
	v_add_f32_dpp v38, v38, v38 row_ror:4 row_mask:0xf bank_mask:0xf bound_ctrl:1
	s_nop 1
	v_add_f32_dpp v38, v38, v38 row_ror:2 row_mask:0xf bank_mask:0xf bound_ctrl:1
	s_nop 1
	v_mov_b32_dpp v39, v38 row_ror:1 row_mask:0xf bank_mask:0xf
	s_and_saveexec_b64 s[18:19], s[4:5]
	s_cbranch_execz .LBB0_804
	s_lshl_b64 s[16:17], s[16:17], 12
	s_add_u32 s16, s22, s16
	s_addc_u32 s17, s23, s17
	s_lshl_b32 s31, s28, 2
	s_add_u32 s16, s16, s31
	s_addc_u32 s17, s17, 0
	v_add_f32_e32 v38, v38, v39
	global_store_dword v29, v38, s[16:17]
